# P0a transpose readout: 16 LDS reads batched per item (was 16 serialized), stores padded for the 128-bit store-data WAR rule
# baseline (speedup 1.0000x reference)
; __device__ __forceinline__ void transpose_item(const float* W, int K, int N, bf16_t* WT, int k0, int n_src, int n_dst, LAS float* scr, int lane) {
; #pragma unroll 8
;     for (int i = 0; i < 32; ++i) { const int kk = 2 * i + (lane >> 5); scr[kk * 33 + (lane & 31)] = W[(size_t)(k0 + kk) * N + n_src + (lane & 31)]; }
.LBB0_34:
	s_lshl_b32 s44, s22, 1
	s_lshl_b32 s45, s23, 1
	v_or_b32_e32 v4, s44, v1
	v_or_b32_e32 v35, s45, v2
	s_add_i32 s46, s44, 4
	s_add_i32 s47, s45, 4
	s_add_i32 s48, s44, 8
	s_add_i32 s49, s45, 8
	s_add_i32 s50, s44, 12
	s_add_i32 s51, s45, 12
	s_add_i32 s52, s44, 16
	s_add_i32 s53, s45, 16
	s_add_i32 s54, s44, 20
	s_add_i32 s55, s45, 20
	s_add_i32 s56, s44, 24
	s_add_i32 s57, s45, 24
	s_add_i32 s44, s44, 28
	s_add_i32 s45, s45, 28
	v_add_u32_e32 v50, v35, v34
	v_or_b32_e32 v47, s46, v1
	v_or_b32_e32 v80, s47, v2
	v_or_b32_e32 v81, s48, v1
	v_or_b32_e32 v82, s49, v2
	v_or_b32_e32 v83, s50, v1
	v_or_b32_e32 v84, s51, v2
	v_or_b32_e32 v85, s52, v1
	v_or_b32_e32 v86, s53, v2
	v_or_b32_e32 v87, s54, v1
	v_or_b32_e32 v88, s55, v2
	v_or_b32_e32 v89, s56, v1
	v_or_b32_e32 v90, s57, v2
	v_or_b32_e32 v91, s44, v1
	v_or_b32_e32 v92, s45, v2
	v_add_u32_e32 v48, v4, v3
	v_ashrrev_i32_e32 v51, 31, v50
	v_add_u32_e32 v52, v47, v3
	v_add_u32_e32 v54, v80, v34
	v_add_u32_e32 v56, v81, v3
	v_add_u32_e32 v58, v82, v34
	v_add_u32_e32 v60, v83, v3
	v_add_u32_e32 v62, v84, v34
	v_add_u32_e32 v64, v85, v3
	v_add_u32_e32 v66, v86, v34
	v_add_u32_e32 v68, v87, v3
	v_add_u32_e32 v70, v88, v34
	v_add_u32_e32 v72, v89, v3
	v_add_u32_e32 v74, v90, v34
	v_add_u32_e32 v76, v91, v3
	v_add_u32_e32 v78, v92, v34
	v_ashrrev_i32_e32 v49, 31, v48
	v_lshlrev_b64 v[50:51], 12, v[50:51]
	v_ashrrev_i32_e32 v55, 31, v54
	v_ashrrev_i32_e32 v53, 31, v52
	v_ashrrev_i32_e32 v59, 31, v58
	v_ashrrev_i32_e32 v57, 31, v56
	v_ashrrev_i32_e32 v63, 31, v62
	v_ashrrev_i32_e32 v61, 31, v60
	v_ashrrev_i32_e32 v67, 31, v66
	v_ashrrev_i32_e32 v65, 31, v64
	v_ashrrev_i32_e32 v71, 31, v70
	v_ashrrev_i32_e32 v69, 31, v68
	v_ashrrev_i32_e32 v75, 31, v74
	v_ashrrev_i32_e32 v73, 31, v72
	v_ashrrev_i32_e32 v79, 31, v78
	v_ashrrev_i32_e32 v77, 31, v76
	v_lshlrev_b64 v[48:49], 12, v[48:49]
	v_lshl_add_u64 v[50:51], v[36:37], 0, v[50:51]
	v_lshlrev_b64 v[52:53], 12, v[52:53]
	v_lshlrev_b64 v[54:55], 12, v[54:55]
	v_lshlrev_b64 v[56:57], 12, v[56:57]
	v_lshlrev_b64 v[58:59], 12, v[58:59]
	v_lshlrev_b64 v[60:61], 12, v[60:61]
	v_lshlrev_b64 v[62:63], 12, v[62:63]
	v_lshlrev_b64 v[64:65], 12, v[64:65]
	v_lshlrev_b64 v[66:67], 12, v[66:67]
	v_lshlrev_b64 v[68:69], 12, v[68:69]
	v_lshlrev_b64 v[70:71], 12, v[70:71]
	v_lshlrev_b64 v[72:73], 12, v[72:73]
	v_lshlrev_b64 v[74:75], 12, v[74:75]
	v_lshlrev_b64 v[76:77], 12, v[76:77]
	v_lshlrev_b64 v[78:79], 12, v[78:79]
	v_lshl_add_u64 v[48:49], v[36:37], 0, v[48:49]
	v_lshl_add_u64 v[54:55], v[36:37], 0, v[54:55]
	v_lshl_add_u64 v[52:53], v[36:37], 0, v[52:53]
	v_lshl_add_u64 v[58:59], v[36:37], 0, v[58:59]
	v_lshl_add_u64 v[56:57], v[36:37], 0, v[56:57]
	v_lshl_add_u64 v[62:63], v[36:37], 0, v[62:63]
	v_lshl_add_u64 v[60:61], v[36:37], 0, v[60:61]
	v_lshl_add_u64 v[66:67], v[36:37], 0, v[66:67]
	v_lshl_add_u64 v[64:65], v[36:37], 0, v[64:65]
	v_lshl_add_u64 v[70:71], v[36:37], 0, v[70:71]
	v_lshl_add_u64 v[68:69], v[36:37], 0, v[68:69]
	v_lshl_add_u64 v[74:75], v[36:37], 0, v[74:75]
	v_lshl_add_u64 v[72:73], v[36:37], 0, v[72:73]
	v_lshl_add_u64 v[78:79], v[36:37], 0, v[78:79]
	v_lshl_add_u64 v[76:77], v[36:37], 0, v[76:77]
	global_load_dword v93, v[50:51], off
	global_load_dword v94, v[48:49], off
	global_load_dword v95, v[54:55], off
	global_load_dword v96, v[52:53], off
	global_load_dword v97, v[58:59], off
	global_load_dword v98, v[56:57], off
	global_load_dword v99, v[62:63], off
	global_load_dword v100, v[60:61], off
	global_load_dword v101, v[66:67], off
	global_load_dword v102, v[64:65], off
	global_load_dword v103, v[70:71], off
	global_load_dword v104, v[68:69], off
	global_load_dword v105, v[74:75], off
	global_load_dword v106, v[72:73], off
	global_load_dword v107, v[78:79], off
	global_load_dword v108, v[76:77], off
	s_add_i32 s23, s23, 16
	s_add_i32 s22, s22, 16
	s_add_i32 s43, s43, -16
	s_cmp_lg_u32 s43, 0
	s_lshl_b32 s44, s22, 1
	s_lshl_b32 s45, s23, 1
	v_or_b32_e32 v174, s44, v1
	v_or_b32_e32 v175, s45, v2
	s_add_i32 s46, s44, 4
	s_add_i32 s47, s45, 4
	s_add_i32 s48, s44, 8
	s_add_i32 s49, s45, 8
	s_add_i32 s50, s44, 12
	s_add_i32 s51, s45, 12
	s_add_i32 s52, s44, 16
	s_add_i32 s53, s45, 16
	s_add_i32 s54, s44, 20
	s_add_i32 s55, s45, 20
	s_add_i32 s56, s44, 24
	s_add_i32 s57, s45, 24
	s_add_i32 s44, s44, 28
	s_add_i32 s45, s45, 28
	v_add_u32_e32 v114, v175, v34
	v_or_b32_e32 v111, s46, v1
	v_or_b32_e32 v144, s47, v2
	v_or_b32_e32 v145, s48, v1
	v_or_b32_e32 v146, s49, v2
	v_or_b32_e32 v147, s50, v1
	v_or_b32_e32 v148, s51, v2
	v_or_b32_e32 v149, s52, v1
	v_or_b32_e32 v150, s53, v2
	v_or_b32_e32 v151, s54, v1
	v_or_b32_e32 v152, s55, v2
	v_or_b32_e32 v153, s56, v1
	v_or_b32_e32 v154, s57, v2
	v_or_b32_e32 v155, s44, v1
	v_or_b32_e32 v156, s45, v2
	v_add_u32_e32 v112, v174, v3
	v_ashrrev_i32_e32 v115, 31, v114
	v_add_u32_e32 v116, v111, v3
	v_add_u32_e32 v118, v144, v34
	v_add_u32_e32 v120, v145, v3
	v_add_u32_e32 v122, v146, v34
	v_add_u32_e32 v124, v147, v3
	v_add_u32_e32 v126, v148, v34
	v_add_u32_e32 v128, v149, v3
	v_add_u32_e32 v130, v150, v34
	v_add_u32_e32 v132, v151, v3
	v_add_u32_e32 v134, v152, v34
	v_add_u32_e32 v136, v153, v3
	v_add_u32_e32 v138, v154, v34
	v_add_u32_e32 v140, v155, v3
	v_add_u32_e32 v142, v156, v34
	v_ashrrev_i32_e32 v113, 31, v112
	v_lshlrev_b64 v[114:115], 12, v[114:115]
	v_ashrrev_i32_e32 v119, 31, v118
	v_ashrrev_i32_e32 v117, 31, v116
	v_ashrrev_i32_e32 v123, 31, v122
	v_ashrrev_i32_e32 v121, 31, v120
	v_ashrrev_i32_e32 v127, 31, v126
	v_ashrrev_i32_e32 v125, 31, v124
	v_ashrrev_i32_e32 v131, 31, v130
	v_ashrrev_i32_e32 v129, 31, v128
	v_ashrrev_i32_e32 v135, 31, v134
	v_ashrrev_i32_e32 v133, 31, v132
; __device__ __forceinline__ void transpose_item(const float* W, int K, int N, bf16_t* WT, int k0, int n_src, int n_dst, LAS float* scr, int lane) {
; #pragma unroll 8
;     for (int i = 0; i < 32; ++i) { const int kk = 2 * i + (lane >> 5); scr[kk * 33 + (lane & 31)] = W[(size_t)(k0 + kk) * N + n_src + (lane & 31)]; }
;     asm volatile("s_waitcnt lgkmcnt(0)" ::: "memory");
	v_ashrrev_i32_e32 v139, 31, v138
	v_ashrrev_i32_e32 v137, 31, v136
	v_ashrrev_i32_e32 v143, 31, v142
	v_ashrrev_i32_e32 v141, 31, v140
	v_lshlrev_b64 v[112:113], 12, v[112:113]
	v_lshl_add_u64 v[114:115], v[36:37], 0, v[114:115]
	v_lshlrev_b64 v[116:117], 12, v[116:117]
	v_lshlrev_b64 v[118:119], 12, v[118:119]
	v_lshlrev_b64 v[120:121], 12, v[120:121]
	v_lshlrev_b64 v[122:123], 12, v[122:123]
	v_lshlrev_b64 v[124:125], 12, v[124:125]
	v_lshlrev_b64 v[126:127], 12, v[126:127]
	v_lshlrev_b64 v[128:129], 12, v[128:129]
	v_lshlrev_b64 v[130:131], 12, v[130:131]
	v_lshlrev_b64 v[132:133], 12, v[132:133]
	v_lshlrev_b64 v[134:135], 12, v[134:135]
	v_lshlrev_b64 v[136:137], 12, v[136:137]
	v_lshlrev_b64 v[138:139], 12, v[138:139]
	v_lshlrev_b64 v[140:141], 12, v[140:141]
	v_lshlrev_b64 v[142:143], 12, v[142:143]
	v_lshl_add_u64 v[112:113], v[36:37], 0, v[112:113]
	v_lshl_add_u64 v[118:119], v[36:37], 0, v[118:119]
	v_lshl_add_u64 v[116:117], v[36:37], 0, v[116:117]
	v_lshl_add_u64 v[122:123], v[36:37], 0, v[122:123]
	v_lshl_add_u64 v[120:121], v[36:37], 0, v[120:121]
	v_lshl_add_u64 v[126:127], v[36:37], 0, v[126:127]
	v_lshl_add_u64 v[124:125], v[36:37], 0, v[124:125]
	v_lshl_add_u64 v[130:131], v[36:37], 0, v[130:131]
	v_lshl_add_u64 v[128:129], v[36:37], 0, v[128:129]
	v_lshl_add_u64 v[134:135], v[36:37], 0, v[134:135]
	v_lshl_add_u64 v[132:133], v[36:37], 0, v[132:133]
	v_lshl_add_u64 v[138:139], v[36:37], 0, v[138:139]
	v_lshl_add_u64 v[136:137], v[36:37], 0, v[136:137]
	v_lshl_add_u64 v[142:143], v[36:37], 0, v[142:143]
	v_lshl_add_u64 v[140:141], v[36:37], 0, v[140:141]
	global_load_dword v157, v[114:115], off
	global_load_dword v158, v[112:113], off
	global_load_dword v159, v[118:119], off
	global_load_dword v160, v[116:117], off
	global_load_dword v161, v[122:123], off
	global_load_dword v162, v[120:121], off
	global_load_dword v163, v[126:127], off
	global_load_dword v164, v[124:125], off
	global_load_dword v165, v[130:131], off
	global_load_dword v166, v[128:129], off
	global_load_dword v167, v[134:135], off
	global_load_dword v168, v[132:133], off
	global_load_dword v169, v[138:139], off
	global_load_dword v170, v[136:137], off
	global_load_dword v171, v[142:143], off
	global_load_dword v172, v[140:141], off
	s_add_i32 s23, s23, 16
	s_add_i32 s22, s22, 16
	s_add_i32 s43, s43, -16
	s_cmp_lg_u32 s43, 0
	v_mad_u64_u32 v[48:49], s[44:45], v35, s24, v[6:7]
	v_mad_u64_u32 v[50:51], s[44:45], v4, s24, v[6:7]
	v_mad_u64_u32 v[52:53], s[44:45], v80, s24, v[6:7]
	v_mad_u64_u32 v[54:55], s[44:45], v47, s24, v[6:7]
	v_mad_u64_u32 v[56:57], s[44:45], v82, s24, v[6:7]
	v_mad_u64_u32 v[58:59], s[44:45], v81, s24, v[6:7]
	v_mad_u64_u32 v[60:61], s[44:45], v84, s24, v[6:7]
	v_mad_u64_u32 v[62:63], s[44:45], v83, s24, v[6:7]
	v_mad_u64_u32 v[64:65], s[44:45], v86, s24, v[6:7]
	v_mad_u64_u32 v[66:67], s[44:45], v85, s24, v[6:7]
	v_mad_u64_u32 v[68:69], s[44:45], v88, s24, v[6:7]
	v_mad_u64_u32 v[70:71], s[44:45], v87, s24, v[6:7]
	v_mad_u64_u32 v[72:73], s[44:45], v90, s24, v[6:7]
	v_mad_u64_u32 v[74:75], s[44:45], v89, s24, v[6:7]
	v_mad_u64_u32 v[76:77], s[44:45], v92, s24, v[6:7]
	v_mad_u64_u32 v[78:79], s[44:45], v91, s24, v[6:7]
	s_waitcnt vmcnt(16)
; #define LAS __attribute__((address_space(3)))
; #define LAS __attribute__((address_space(3)))
; __device__ __forceinline__ unsigned pkbf(float lo, float hi) { return pg8::cvt_pk_bf16(lo, hi); }
; __device__ __forceinline__ void transpose_item(const float* W, int K, int N, bf16_t* WT, int k0, int n_src, int n_dst, LAS float* scr, int lane) {
;     ...
;     for (int i = 0; i < 32; ++i) { const int kk = 2 * i + (lane >> 5); scr[kk * 33 + (lane & 31)] = W[(size_t)(k0 + kk) * N + n_src + (lane & 31)]; }
;     asm volatile("s_waitcnt lgkmcnt(0)" ::: "memory");
;     const int c = lane & 7;
; #pragma unroll
;     for (int j = 0; j < 4; ++j) {
;         const int n = (lane >> 3) + 8 * j; const LAS float* s = scr + (8 * c) * 33 + n;
;         u32x4 o; o.x = pkbf(s[0 * 33], s[1 * 33]); o.y = pkbf(s[2 * 33], s[3 * 33]); o.z = pkbf(s[4 * 33], s[5 * 33]); o.w = pkbf(s[6 * 33], s[7 * 33]);
;         *(u32x4*)(WT + (size_t)(n_dst + n) * K + k0 + 8 * c) = o;
;     }
;     asm volatile("s_waitcnt lgkmcnt(0)" ::: "memory");
	ds_write_b32 v48, v93
	ds_write_b32 v50, v94
	ds_write_b32 v52, v95
	ds_write_b32 v54, v96
	ds_write_b32 v56, v97
	ds_write_b32 v58, v98
	ds_write_b32 v60, v99
	ds_write_b32 v62, v100
	ds_write_b32 v64, v101
	ds_write_b32 v66, v102
	ds_write_b32 v68, v103
	ds_write_b32 v70, v104
	ds_write_b32 v72, v105
	ds_write_b32 v74, v106
	ds_write_b32 v76, v107
	ds_write_b32 v78, v108
	v_mad_u64_u32 v[112:113], s[44:45], v175, s24, v[6:7]
	v_mad_u64_u32 v[114:115], s[44:45], v174, s24, v[6:7]
	v_mad_u64_u32 v[116:117], s[44:45], v144, s24, v[6:7]
	v_mad_u64_u32 v[118:119], s[44:45], v111, s24, v[6:7]
	v_mad_u64_u32 v[120:121], s[44:45], v146, s24, v[6:7]
	v_mad_u64_u32 v[122:123], s[44:45], v145, s24, v[6:7]
	v_mad_u64_u32 v[124:125], s[44:45], v148, s24, v[6:7]
	v_mad_u64_u32 v[126:127], s[44:45], v147, s24, v[6:7]
	v_mad_u64_u32 v[128:129], s[44:45], v150, s24, v[6:7]
	v_mad_u64_u32 v[130:131], s[44:45], v149, s24, v[6:7]
	v_mad_u64_u32 v[132:133], s[44:45], v152, s24, v[6:7]
	v_mad_u64_u32 v[134:135], s[44:45], v151, s24, v[6:7]
	v_mad_u64_u32 v[136:137], s[44:45], v154, s24, v[6:7]
	v_mad_u64_u32 v[138:139], s[44:45], v153, s24, v[6:7]
	v_mad_u64_u32 v[140:141], s[44:45], v156, s24, v[6:7]
	v_mad_u64_u32 v[142:143], s[44:45], v155, s24, v[6:7]
	s_waitcnt vmcnt(0)
	ds_write_b32 v112, v157
	ds_write_b32 v114, v158
	ds_write_b32 v116, v159
	ds_write_b32 v118, v160
	ds_write_b32 v120, v161
	ds_write_b32 v122, v162
	ds_write_b32 v124, v163
	ds_write_b32 v126, v164
	ds_write_b32 v128, v165
	ds_write_b32 v130, v166
	ds_write_b32 v132, v167
	ds_write_b32 v134, v168
	ds_write_b32 v136, v169
	ds_write_b32 v138, v170
	ds_write_b32 v140, v171
	ds_write_b32 v142, v172
	s_waitcnt lgkmcnt(0)
	ds_read2_b32 v[110:111], v38 offset1:33
	ds_read2_b32 v[112:113], v38 offset0:66 offset1:99
	ds_read2_b32 v[114:115], v38 offset0:132 offset1:165
	ds_read2_b32 v[116:117], v38 offset0:198 offset1:231
	ds_read2_b32 v[118:119], v38 offset0:8 offset1:41
	ds_read2_b32 v[120:121], v38 offset0:74 offset1:107
	ds_read2_b32 v[122:123], v38 offset0:140 offset1:173
	ds_read2_b32 v[124:125], v38 offset0:206 offset1:239
	ds_read2_b32 v[126:127], v38 offset0:16 offset1:49
	ds_read2_b32 v[128:129], v38 offset0:82 offset1:115
	ds_read2_b32 v[130:131], v38 offset0:148 offset1:181
	ds_read2_b32 v[132:133], v38 offset0:214 offset1:247
	ds_read2_b32 v[134:135], v38 offset0:24 offset1:57
	ds_read2_b32 v[136:137], v38 offset0:90 offset1:123
	ds_read2_b32 v[138:139], v38 offset0:156 offset1:189
	ds_read2_b32 v[140:141], v38 offset0:222 offset1:255
	s_waitcnt lgkmcnt(0)
	v_cvt_pk_bf16_f32 v48, v110, v111
	v_or_b32_e32 v3, v46, v7
	v_cvt_pk_bf16_f32 v49, v112, v113
	v_mov_b32_e32 v35, v5
	v_mul_u32_u24_e32 v3, 0xb00, v3
	v_cvt_pk_bf16_f32 v50, v114, v115
	v_lshl_add_u64 v[52:53], v[34:35], 1, v[20:21]
	v_lshlrev_b32_e32 v4, 1, v3
	v_cvt_pk_bf16_f32 v51, v116, v117
	v_lshl_add_u64 v[36:37], v[52:53], 0, v[4:5]
	v_or_b32_e32 v3, v46, v39
	global_store_dwordx4 v[36:37], v[48:51], off
	s_nop 1
	v_cvt_pk_bf16_f32 v34, v118, v119
	v_mul_u32_u24_e32 v3, 0xb00, v3
	v_cvt_pk_bf16_f32 v35, v120, v121
	v_lshlrev_b32_e32 v4, 1, v3
	v_cvt_pk_bf16_f32 v36, v122, v123
	v_cvt_pk_bf16_f32 v37, v124, v125
	v_lshl_add_u64 v[50:51], v[52:53], 0, v[4:5]
	v_or_b32_e32 v3, v46, v40
	global_store_dwordx4 v[50:51], v[34:37], off
	s_nop 1
	v_mul_u32_u24_e32 v3, 0xb00, v3
	v_lshlrev_b32_e32 v4, 1, v3
	v_cvt_pk_bf16_f32 v34, v126, v127
	v_cvt_pk_bf16_f32 v35, v128, v129
	v_or_b32_e32 v3, v46, v41
	v_cvt_pk_bf16_f32 v36, v130, v131
	v_cvt_pk_bf16_f32 v37, v132, v133
	v_lshl_add_u64 v[50:51], v[52:53], 0, v[4:5]
	v_mul_u32_u24_e32 v3, 0xb00, v3
	global_store_dwordx4 v[50:51], v[34:37], off
	s_nop 1
	v_lshlrev_b32_e32 v4, 1, v3
	v_lshl_add_u64 v[46:47], v[52:53], 0, v[4:5]
	v_cvt_pk_bf16_f32 v34, v134, v135
	v_cvt_pk_bf16_f32 v35, v136, v137
	v_cvt_pk_bf16_f32 v36, v138, v139
	v_cvt_pk_bf16_f32 v37, v140, v141
	global_store_dwordx4 v[46:47], v[34:37], off
	s_nop 1
	s_waitcnt lgkmcnt(0)

; __device__ __forceinline__ void transpose_item(const float* W, int K, int N, bf16_t* WT, int k0, int n_src, int n_dst, LAS float* scr, int lane) {
; #pragma unroll 8
;     for (int i = 0; i < 32; ++i) { const int kk = 2 * i + (lane >> 5); scr[kk * 33 + (lane & 31)] = W[(size_t)(k0 + kk) * N + n_src + (lane & 31)]; }
.LBB0_38:
	s_lshl_b32 s44, s43, 1
	s_lshl_b32 s45, s0, 1
	v_or_b32_e32 v4, s44, v1
	v_or_b32_e32 v78, s45, v2
	s_add_i32 s46, s44, 4
	s_add_i32 s47, s45, 4
	s_add_i32 s48, s44, 8
	s_add_i32 s49, s45, 8
	s_add_i32 s50, s44, 12
	s_add_i32 s51, s45, 12
	s_add_i32 s52, s44, 16
	s_add_i32 s53, s45, 16
	s_add_i32 s54, s44, 20
	s_add_i32 s55, s45, 20
	s_add_i32 s56, s44, 24
	s_add_i32 s57, s45, 24
	s_add_i32 s44, s44, 28
	s_add_i32 s45, s45, 28
	v_add_u32_e32 v46, v78, v34
	v_or_b32_e32 v79, s46, v1
	v_or_b32_e32 v80, s47, v2
	v_or_b32_e32 v81, s48, v1
	v_or_b32_e32 v82, s49, v2
	v_or_b32_e32 v83, s50, v1
	v_or_b32_e32 v84, s51, v2
	v_or_b32_e32 v85, s52, v1
	v_or_b32_e32 v86, s53, v2
	v_or_b32_e32 v87, s54, v1
	v_or_b32_e32 v88, s55, v2
	v_or_b32_e32 v89, s56, v1
	v_or_b32_e32 v90, s57, v2
	v_or_b32_e32 v91, s44, v1
	v_or_b32_e32 v92, s45, v2
	v_add_u32_e32 v48, v4, v3
	v_mad_u64_u32 v[46:47], s[44:45], v46, s34, v[36:37]
	v_add_u32_e32 v52, v79, v3
	v_add_u32_e32 v50, v80, v34
	v_add_u32_e32 v56, v81, v3
	v_add_u32_e32 v54, v82, v34
	v_add_u32_e32 v60, v83, v3
	v_add_u32_e32 v58, v84, v34
	v_add_u32_e32 v64, v85, v3
	v_add_u32_e32 v62, v86, v34
	v_add_u32_e32 v68, v87, v3
	v_add_u32_e32 v66, v88, v34
	v_add_u32_e32 v72, v89, v3
	v_add_u32_e32 v70, v90, v34
	v_add_u32_e32 v76, v91, v3
	v_add_u32_e32 v74, v92, v34
	v_mad_u64_u32 v[48:49], s[44:45], v48, s34, v[36:37]
	v_mad_u64_u32 v[50:51], s[44:45], v50, s34, v[36:37]
	v_mad_u64_u32 v[52:53], s[44:45], v52, s34, v[36:37]
	v_mad_u64_u32 v[54:55], s[44:45], v54, s34, v[36:37]
	v_mad_u64_u32 v[56:57], s[44:45], v56, s34, v[36:37]
	v_mad_u64_u32 v[58:59], s[44:45], v58, s34, v[36:37]
	v_mad_u64_u32 v[60:61], s[44:45], v60, s34, v[36:37]
	v_mad_u64_u32 v[62:63], s[44:45], v62, s34, v[36:37]
	v_mad_u64_u32 v[64:65], s[44:45], v64, s34, v[36:37]
	v_mad_u64_u32 v[66:67], s[44:45], v66, s34, v[36:37]
	v_mad_u64_u32 v[68:69], s[44:45], v68, s34, v[36:37]
	v_mad_u64_u32 v[70:71], s[44:45], v70, s34, v[36:37]
	v_mad_u64_u32 v[72:73], s[44:45], v72, s34, v[36:37]
	v_mad_u64_u32 v[74:75], s[44:45], v74, s34, v[36:37]
	v_mad_u64_u32 v[76:77], s[44:45], v76, s34, v[36:37]
	global_load_dword v93, v[46:47], off
	global_load_dword v94, v[48:49], off
	global_load_dword v95, v[50:51], off
	global_load_dword v96, v[52:53], off
	global_load_dword v97, v[54:55], off
	global_load_dword v98, v[56:57], off
	global_load_dword v99, v[58:59], off
	global_load_dword v100, v[60:61], off
	global_load_dword v101, v[62:63], off
	global_load_dword v102, v[64:65], off
	global_load_dword v103, v[66:67], off
	global_load_dword v104, v[68:69], off
	global_load_dword v105, v[70:71], off
	global_load_dword v106, v[72:73], off
	global_load_dword v107, v[74:75], off
	global_load_dword v108, v[76:77], off
	s_add_i32 s0, s0, 16
	s_add_i32 s43, s43, 16
	s_add_i32 s1, s1, -16
	s_cmp_lg_u32 s1, 0
	s_lshl_b32 s44, s43, 1
	s_lshl_b32 s45, s0, 1
	v_or_b32_e32 v174, s44, v1
	v_or_b32_e32 v142, s45, v2
	s_add_i32 s46, s44, 4
	s_add_i32 s47, s45, 4
	s_add_i32 s48, s44, 8
	s_add_i32 s49, s45, 8
	s_add_i32 s50, s44, 12
	s_add_i32 s51, s45, 12
	s_add_i32 s52, s44, 16
	s_add_i32 s53, s45, 16
	s_add_i32 s54, s44, 20
	s_add_i32 s55, s45, 20
	s_add_i32 s56, s44, 24
	s_add_i32 s57, s45, 24
	s_add_i32 s44, s44, 28
	s_add_i32 s45, s45, 28
	v_add_u32_e32 v110, v142, v34
	v_or_b32_e32 v143, s46, v1
	v_or_b32_e32 v144, s47, v2
	v_or_b32_e32 v145, s48, v1
	v_or_b32_e32 v146, s49, v2
	v_or_b32_e32 v147, s50, v1
	v_or_b32_e32 v148, s51, v2
	v_or_b32_e32 v149, s52, v1
	v_or_b32_e32 v150, s53, v2
	v_or_b32_e32 v151, s54, v1
	v_or_b32_e32 v152, s55, v2
	v_or_b32_e32 v153, s56, v1
	v_or_b32_e32 v154, s57, v2
	v_or_b32_e32 v155, s44, v1
	v_or_b32_e32 v156, s45, v2
	v_add_u32_e32 v112, v174, v3
	v_mad_u64_u32 v[110:111], s[44:45], v110, s34, v[36:37]
	v_add_u32_e32 v116, v143, v3
	v_add_u32_e32 v114, v144, v34
	v_add_u32_e32 v120, v145, v3
	v_add_u32_e32 v118, v146, v34
	v_add_u32_e32 v124, v147, v3
	v_add_u32_e32 v122, v148, v34
	v_add_u32_e32 v128, v149, v3
	v_add_u32_e32 v126, v150, v34
	v_add_u32_e32 v132, v151, v3
	v_add_u32_e32 v130, v152, v34
	v_add_u32_e32 v136, v153, v3
	v_add_u32_e32 v134, v154, v34
	v_add_u32_e32 v140, v155, v3
	v_add_u32_e32 v138, v156, v34
	v_mad_u64_u32 v[112:113], s[44:45], v112, s34, v[36:37]
	v_mad_u64_u32 v[114:115], s[44:45], v114, s34, v[36:37]
	v_mad_u64_u32 v[116:117], s[44:45], v116, s34, v[36:37]
	v_mad_u64_u32 v[118:119], s[44:45], v118, s34, v[36:37]
	v_mad_u64_u32 v[120:121], s[44:45], v120, s34, v[36:37]
	v_mad_u64_u32 v[122:123], s[44:45], v122, s34, v[36:37]
	v_mad_u64_u32 v[124:125], s[44:45], v124, s34, v[36:37]
	v_mad_u64_u32 v[126:127], s[44:45], v126, s34, v[36:37]
	v_mad_u64_u32 v[128:129], s[44:45], v128, s34, v[36:37]
	v_mad_u64_u32 v[130:131], s[44:45], v130, s34, v[36:37]
	v_mad_u64_u32 v[132:133], s[44:45], v132, s34, v[36:37]
	v_mad_u64_u32 v[134:135], s[44:45], v134, s34, v[36:37]
	v_mad_u64_u32 v[136:137], s[44:45], v136, s34, v[36:37]
	v_mad_u64_u32 v[138:139], s[44:45], v138, s34, v[36:37]
	v_mad_u64_u32 v[140:141], s[44:45], v140, s34, v[36:37]
	global_load_dword v157, v[110:111], off
	global_load_dword v158, v[112:113], off
	global_load_dword v159, v[114:115], off
	global_load_dword v160, v[116:117], off
	global_load_dword v161, v[118:119], off
	global_load_dword v162, v[120:121], off
	global_load_dword v163, v[122:123], off
	global_load_dword v164, v[124:125], off
	global_load_dword v165, v[126:127], off
	global_load_dword v166, v[128:129], off
	global_load_dword v167, v[130:131], off
	global_load_dword v168, v[132:133], off
	global_load_dword v169, v[134:135], off
	global_load_dword v170, v[136:137], off
	global_load_dword v171, v[138:139], off
	global_load_dword v172, v[140:141], off
	s_add_i32 s0, s0, 16
	s_add_i32 s43, s43, 16
	s_add_i32 s1, s1, -16
	s_cmp_lg_u32 s1, 0
	v_mad_u64_u32 v[46:47], s[44:45], v78, s24, v[6:7]
	v_mad_u64_u32 v[48:49], s[44:45], v4, s24, v[6:7]
	v_mad_u64_u32 v[50:51], s[44:45], v80, s24, v[6:7]
	v_mad_u64_u32 v[52:53], s[44:45], v79, s24, v[6:7]
	v_mad_u64_u32 v[54:55], s[44:45], v82, s24, v[6:7]
	v_mad_u64_u32 v[56:57], s[44:45], v81, s24, v[6:7]
	v_mad_u64_u32 v[58:59], s[44:45], v84, s24, v[6:7]
	v_mad_u64_u32 v[60:61], s[44:45], v83, s24, v[6:7]
	v_mad_u64_u32 v[62:63], s[44:45], v86, s24, v[6:7]
	v_mad_u64_u32 v[64:65], s[44:45], v85, s24, v[6:7]
	v_mad_u64_u32 v[66:67], s[44:45], v88, s24, v[6:7]
	v_mad_u64_u32 v[68:69], s[44:45], v87, s24, v[6:7]
	v_mad_u64_u32 v[70:71], s[44:45], v90, s24, v[6:7]
	v_mad_u64_u32 v[72:73], s[44:45], v89, s24, v[6:7]
	v_mad_u64_u32 v[74:75], s[44:45], v92, s24, v[6:7]
	v_mad_u64_u32 v[76:77], s[44:45], v91, s24, v[6:7]
	s_waitcnt vmcnt(16)
; #define LAS __attribute__((address_space(3)))
; #define LAS __attribute__((address_space(3)))
; __device__ __forceinline__ unsigned pkbf(float lo, float hi) { return pg8::cvt_pk_bf16(lo, hi); }
; __device__ __forceinline__ void transpose_item(const float* W, int K, int N, bf16_t* WT, int k0, int n_src, int n_dst, LAS float* scr, int lane) {
;     ...
;     for (int i = 0; i < 32; ++i) { const int kk = 2 * i + (lane >> 5); scr[kk * 33 + (lane & 31)] = W[(size_t)(k0 + kk) * N + n_src + (lane & 31)]; }
;     asm volatile("s_waitcnt lgkmcnt(0)" ::: "memory");
;     const int c = lane & 7;
; #pragma unroll
;     for (int j = 0; j < 4; ++j) {
;         const int n = (lane >> 3) + 8 * j; const LAS float* s = scr + (8 * c) * 33 + n;
;         u32x4 o; o.x = pkbf(s[0 * 33], s[1 * 33]); o.y = pkbf(s[2 * 33], s[3 * 33]); o.z = pkbf(s[4 * 33], s[5 * 33]); o.w = pkbf(s[6 * 33], s[7 * 33]);
;         *(u32x4*)(WT + (size_t)(n_dst + n) * K + k0 + 8 * c) = o;
;     }
;     asm volatile("s_waitcnt lgkmcnt(0)" ::: "memory");
	ds_write_b32 v46, v93
	ds_write_b32 v48, v94
	ds_write_b32 v50, v95
	ds_write_b32 v52, v96
	ds_write_b32 v54, v97
	ds_write_b32 v56, v98
	ds_write_b32 v58, v99
	ds_write_b32 v60, v100
	ds_write_b32 v62, v101
	ds_write_b32 v64, v102
	ds_write_b32 v66, v103
	ds_write_b32 v68, v104
	ds_write_b32 v70, v105
	ds_write_b32 v72, v106
	ds_write_b32 v74, v107
	ds_write_b32 v76, v108
	v_mad_u64_u32 v[110:111], s[44:45], v142, s24, v[6:7]
	v_mad_u64_u32 v[112:113], s[44:45], v174, s24, v[6:7]
	v_mad_u64_u32 v[114:115], s[44:45], v144, s24, v[6:7]
	v_mad_u64_u32 v[116:117], s[44:45], v143, s24, v[6:7]
	v_mad_u64_u32 v[118:119], s[44:45], v146, s24, v[6:7]
	v_mad_u64_u32 v[120:121], s[44:45], v145, s24, v[6:7]
	v_mad_u64_u32 v[122:123], s[44:45], v148, s24, v[6:7]
	v_mad_u64_u32 v[124:125], s[44:45], v147, s24, v[6:7]
	v_mad_u64_u32 v[126:127], s[44:45], v150, s24, v[6:7]
	v_mad_u64_u32 v[128:129], s[44:45], v149, s24, v[6:7]
	v_mad_u64_u32 v[130:131], s[44:45], v152, s24, v[6:7]
	v_mad_u64_u32 v[132:133], s[44:45], v151, s24, v[6:7]
	v_mad_u64_u32 v[134:135], s[44:45], v154, s24, v[6:7]
	v_mad_u64_u32 v[136:137], s[44:45], v153, s24, v[6:7]
	v_mad_u64_u32 v[138:139], s[44:45], v156, s24, v[6:7]
	v_mad_u64_u32 v[140:141], s[44:45], v155, s24, v[6:7]
	s_waitcnt vmcnt(0)
	ds_write_b32 v110, v157
	ds_write_b32 v112, v158
	ds_write_b32 v114, v159
	ds_write_b32 v116, v160
	ds_write_b32 v118, v161
	ds_write_b32 v120, v162
	ds_write_b32 v122, v163
	ds_write_b32 v124, v164
	ds_write_b32 v126, v165
	ds_write_b32 v128, v166
	ds_write_b32 v130, v167
	ds_write_b32 v132, v168
	ds_write_b32 v134, v169
	ds_write_b32 v136, v170
	ds_write_b32 v138, v171
	ds_write_b32 v140, v172
	s_waitcnt lgkmcnt(0)
	ds_read2_b32 v[110:111], v38 offset1:33
	ds_read2_b32 v[112:113], v38 offset0:66 offset1:99
	ds_read2_b32 v[114:115], v38 offset0:132 offset1:165
	ds_read2_b32 v[116:117], v38 offset0:198 offset1:231
	ds_read2_b32 v[118:119], v38 offset0:8 offset1:41
	ds_read2_b32 v[120:121], v38 offset0:74 offset1:107
	ds_read2_b32 v[122:123], v38 offset0:140 offset1:173
	ds_read2_b32 v[124:125], v38 offset0:206 offset1:239
	ds_read2_b32 v[126:127], v38 offset0:16 offset1:49
	ds_read2_b32 v[128:129], v38 offset0:82 offset1:115
	ds_read2_b32 v[130:131], v38 offset0:148 offset1:181
	ds_read2_b32 v[132:133], v38 offset0:214 offset1:247
	ds_read2_b32 v[134:135], v38 offset0:24 offset1:57
	ds_read2_b32 v[136:137], v38 offset0:90 offset1:123
	ds_read2_b32 v[138:139], v38 offset0:156 offset1:189
	ds_read2_b32 v[140:141], v38 offset0:222 offset1:255
	s_waitcnt lgkmcnt(0)
	v_cvt_pk_bf16_f32 v46, v110, v111
	v_cvt_pk_bf16_f32 v47, v112, v113
	v_lshlrev_b32_e32 v4, 1, v34
	v_or_b32_e32 v3, v7, v35
	v_cvt_pk_bf16_f32 v48, v114, v115
	v_lshl_add_u64 v[50:51], v[22:23], 0, v[4:5]
	v_lshlrev_b32_e32 v4, 11, v3
	v_cvt_pk_bf16_f32 v49, v116, v117
	v_lshl_add_u64 v[52:53], v[50:51], 0, v[4:5]
	global_store_dwordx4 v[52:53], v[46:49], off
	s_nop 1
	v_or_b32_e32 v3, v39, v35
	v_lshlrev_b32_e32 v4, 11, v3
	v_cvt_pk_bf16_f32 v46, v118, v119
	v_cvt_pk_bf16_f32 v47, v120, v121
	v_cvt_pk_bf16_f32 v48, v122, v123
	v_cvt_pk_bf16_f32 v49, v124, v125
	v_lshl_add_u64 v[52:53], v[50:51], 0, v[4:5]
	global_store_dwordx4 v[52:53], v[46:49], off
	s_nop 1
	v_or_b32_e32 v3, v40, v35
	v_lshlrev_b32_e32 v4, 11, v3
	v_cvt_pk_bf16_f32 v46, v126, v127
	v_cvt_pk_bf16_f32 v47, v128, v129
	v_cvt_pk_bf16_f32 v48, v130, v131
	v_cvt_pk_bf16_f32 v49, v132, v133
	v_lshl_add_u64 v[52:53], v[50:51], 0, v[4:5]
	v_or_b32_e32 v3, v41, v35
	global_store_dwordx4 v[52:53], v[46:49], off
	s_nop 1
	v_lshlrev_b32_e32 v4, 11, v3
	v_lshl_add_u64 v[34:35], v[50:51], 0, v[4:5]
	v_cvt_pk_bf16_f32 v46, v134, v135
	v_cvt_pk_bf16_f32 v47, v136, v137
	v_cvt_pk_bf16_f32 v48, v138, v139
	v_cvt_pk_bf16_f32 v49, v140, v141
	global_store_dwordx4 v[34:35], v[46:49], off
	s_nop 1
	s_waitcnt lgkmcnt(0)

; __device__ __forceinline__ void transpose_item(const float* W, int K, int N, bf16_t* WT, int k0, int n_src, int n_dst, LAS float* scr, int lane) {
; #pragma unroll 8
;     for (int i = 0; i < 32; ++i) { const int kk = 2 * i + (lane >> 5); scr[kk * 33 + (lane & 31)] = W[(size_t)(k0 + kk) * N + n_src + (lane & 31)]; }
.LBB0_43:
	s_lshl_b32 s23, s20, 1
	s_lshl_b32 s43, s21, 1
	v_or_b32_e32 v4, s23, v1
	v_or_b32_e32 v35, s43, v2
	s_add_i32 s44, s23, 4
	s_add_i32 s45, s43, 4
	s_add_i32 s46, s23, 8
	s_add_i32 s47, s43, 8
	s_add_i32 s48, s23, 12
	s_add_i32 s49, s43, 12
	s_add_i32 s50, s23, 16
	s_add_i32 s51, s43, 16
	s_add_i32 s52, s23, 20
	s_add_i32 s53, s43, 20
	s_add_i32 s54, s23, 24
	s_add_i32 s55, s43, 24
	s_add_i32 s23, s23, 28
	s_add_i32 s43, s43, 28
	v_add_u32_e32 v50, v35, v34
	v_or_b32_e32 v47, s44, v1
	v_or_b32_e32 v80, s45, v2
	v_or_b32_e32 v81, s46, v1
	v_or_b32_e32 v82, s47, v2
	v_or_b32_e32 v83, s48, v1
	v_or_b32_e32 v84, s49, v2
	v_or_b32_e32 v85, s50, v1
	v_or_b32_e32 v86, s51, v2
	v_or_b32_e32 v87, s52, v1
	v_or_b32_e32 v88, s53, v2
	v_or_b32_e32 v89, s54, v1
	v_or_b32_e32 v90, s55, v2
	v_or_b32_e32 v91, s23, v1
	v_or_b32_e32 v92, s43, v2
	v_add_u32_e32 v48, v4, v3
	v_ashrrev_i32_e32 v51, 31, v50
	v_add_u32_e32 v52, v47, v3
	v_add_u32_e32 v54, v80, v34
	v_add_u32_e32 v56, v81, v3
	v_add_u32_e32 v58, v82, v34
	v_add_u32_e32 v60, v83, v3
	v_add_u32_e32 v62, v84, v34
	v_add_u32_e32 v64, v85, v3
	v_add_u32_e32 v66, v86, v34
	v_add_u32_e32 v68, v87, v3
	v_add_u32_e32 v70, v88, v34
	v_add_u32_e32 v72, v89, v3
	v_add_u32_e32 v74, v90, v34
	v_add_u32_e32 v76, v91, v3
	v_add_u32_e32 v78, v92, v34
	v_ashrrev_i32_e32 v49, 31, v48
	v_lshlrev_b64 v[50:51], 12, v[50:51]
	v_ashrrev_i32_e32 v55, 31, v54
	v_ashrrev_i32_e32 v53, 31, v52
	v_ashrrev_i32_e32 v59, 31, v58
	v_ashrrev_i32_e32 v57, 31, v56
	v_ashrrev_i32_e32 v63, 31, v62
	v_ashrrev_i32_e32 v61, 31, v60
	v_ashrrev_i32_e32 v67, 31, v66
	v_ashrrev_i32_e32 v65, 31, v64
	v_ashrrev_i32_e32 v71, 31, v70
	v_ashrrev_i32_e32 v69, 31, v68
	v_ashrrev_i32_e32 v75, 31, v74
	v_ashrrev_i32_e32 v73, 31, v72
	v_ashrrev_i32_e32 v79, 31, v78
	v_ashrrev_i32_e32 v77, 31, v76
	v_lshlrev_b64 v[48:49], 12, v[48:49]
	v_lshl_add_u64 v[50:51], v[36:37], 0, v[50:51]
	v_lshlrev_b64 v[52:53], 12, v[52:53]
	v_lshlrev_b64 v[54:55], 12, v[54:55]
	v_lshlrev_b64 v[56:57], 12, v[56:57]
	v_lshlrev_b64 v[58:59], 12, v[58:59]
	v_lshlrev_b64 v[60:61], 12, v[60:61]
	v_lshlrev_b64 v[62:63], 12, v[62:63]
	v_lshlrev_b64 v[64:65], 12, v[64:65]
	v_lshlrev_b64 v[66:67], 12, v[66:67]
	v_lshlrev_b64 v[68:69], 12, v[68:69]
	v_lshlrev_b64 v[70:71], 12, v[70:71]
	v_lshlrev_b64 v[72:73], 12, v[72:73]
	v_lshlrev_b64 v[74:75], 12, v[74:75]
	v_lshlrev_b64 v[76:77], 12, v[76:77]
	v_lshlrev_b64 v[78:79], 12, v[78:79]
	v_lshl_add_u64 v[48:49], v[36:37], 0, v[48:49]
	v_lshl_add_u64 v[54:55], v[36:37], 0, v[54:55]
	v_lshl_add_u64 v[52:53], v[36:37], 0, v[52:53]
	v_lshl_add_u64 v[58:59], v[36:37], 0, v[58:59]
	v_lshl_add_u64 v[56:57], v[36:37], 0, v[56:57]
	v_lshl_add_u64 v[62:63], v[36:37], 0, v[62:63]
	v_lshl_add_u64 v[60:61], v[36:37], 0, v[60:61]
	v_lshl_add_u64 v[66:67], v[36:37], 0, v[66:67]
	v_lshl_add_u64 v[64:65], v[36:37], 0, v[64:65]
	v_lshl_add_u64 v[70:71], v[36:37], 0, v[70:71]
	v_lshl_add_u64 v[68:69], v[36:37], 0, v[68:69]
	v_lshl_add_u64 v[74:75], v[36:37], 0, v[74:75]
	v_lshl_add_u64 v[72:73], v[36:37], 0, v[72:73]
	v_lshl_add_u64 v[78:79], v[36:37], 0, v[78:79]
	v_lshl_add_u64 v[76:77], v[36:37], 0, v[76:77]
	global_load_dword v93, v[50:51], off
	global_load_dword v94, v[48:49], off
	global_load_dword v95, v[54:55], off
	global_load_dword v96, v[52:53], off
	global_load_dword v97, v[58:59], off
	global_load_dword v98, v[56:57], off
	global_load_dword v99, v[62:63], off
	global_load_dword v100, v[60:61], off
	global_load_dword v101, v[66:67], off
	global_load_dword v102, v[64:65], off
	global_load_dword v103, v[70:71], off
	global_load_dword v104, v[68:69], off
	global_load_dword v105, v[74:75], off
	global_load_dword v106, v[72:73], off
	global_load_dword v107, v[78:79], off
	global_load_dword v108, v[76:77], off
	s_add_i32 s21, s21, 16
	s_add_i32 s20, s20, 16
	s_add_i32 s22, s22, -16
	s_cmp_lg_u32 s22, 0
	s_lshl_b32 s23, s20, 1
	s_lshl_b32 s43, s21, 1
	v_or_b32_e32 v174, s23, v1
	v_or_b32_e32 v175, s43, v2
	s_add_i32 s44, s23, 4
	s_add_i32 s45, s43, 4
	s_add_i32 s46, s23, 8
	s_add_i32 s47, s43, 8
	s_add_i32 s48, s23, 12
	s_add_i32 s49, s43, 12
	s_add_i32 s50, s23, 16
	s_add_i32 s51, s43, 16
	s_add_i32 s52, s23, 20
	s_add_i32 s53, s43, 20
	s_add_i32 s54, s23, 24
	s_add_i32 s55, s43, 24
	s_add_i32 s23, s23, 28
	s_add_i32 s43, s43, 28
	v_add_u32_e32 v114, v175, v34
	v_or_b32_e32 v111, s44, v1
	v_or_b32_e32 v144, s45, v2
	v_or_b32_e32 v145, s46, v1
	v_or_b32_e32 v146, s47, v2
	v_or_b32_e32 v147, s48, v1
	v_or_b32_e32 v148, s49, v2
	v_or_b32_e32 v149, s50, v1
	v_or_b32_e32 v150, s51, v2
	v_or_b32_e32 v151, s52, v1
	v_or_b32_e32 v152, s53, v2
	v_or_b32_e32 v153, s54, v1
	v_or_b32_e32 v154, s55, v2
	v_or_b32_e32 v155, s23, v1
	v_or_b32_e32 v156, s43, v2
	v_add_u32_e32 v112, v174, v3
	v_ashrrev_i32_e32 v115, 31, v114
	v_add_u32_e32 v116, v111, v3
	v_add_u32_e32 v118, v144, v34
	v_add_u32_e32 v120, v145, v3
	v_add_u32_e32 v122, v146, v34
	v_add_u32_e32 v124, v147, v3
	v_add_u32_e32 v126, v148, v34
	v_add_u32_e32 v128, v149, v3
	v_add_u32_e32 v130, v150, v34
	v_add_u32_e32 v132, v151, v3
	v_add_u32_e32 v134, v152, v34
	v_add_u32_e32 v136, v153, v3
	v_add_u32_e32 v138, v154, v34
	v_add_u32_e32 v140, v155, v3
	v_add_u32_e32 v142, v156, v34
	v_ashrrev_i32_e32 v113, 31, v112
	v_lshlrev_b64 v[114:115], 12, v[114:115]
	v_ashrrev_i32_e32 v119, 31, v118
	v_ashrrev_i32_e32 v117, 31, v116
	v_ashrrev_i32_e32 v123, 31, v122
	v_ashrrev_i32_e32 v121, 31, v120
	v_ashrrev_i32_e32 v127, 31, v126
	v_ashrrev_i32_e32 v125, 31, v124
	v_ashrrev_i32_e32 v131, 31, v130
	v_ashrrev_i32_e32 v129, 31, v128
	v_ashrrev_i32_e32 v135, 31, v134
	v_ashrrev_i32_e32 v133, 31, v132
; #define LAS __attribute__((address_space(3)))
; #define LAS __attribute__((address_space(3)))
; __device__ __forceinline__ unsigned pkbf(float lo, float hi) { return pg8::cvt_pk_bf16(lo, hi); }
; __device__ __forceinline__ void transpose_item(const float* W, int K, int N, bf16_t* WT, int k0, int n_src, int n_dst, LAS float* scr, int lane) {
;     ...
;     for (int i = 0; i < 32; ++i) { const int kk = 2 * i + (lane >> 5); scr[kk * 33 + (lane & 31)] = W[(size_t)(k0 + kk) * N + n_src + (lane & 31)]; }
;     asm volatile("s_waitcnt lgkmcnt(0)" ::: "memory");
;     const int c = lane & 7;
; #pragma unroll
;     for (int j = 0; j < 4; ++j) {
;         const int n = (lane >> 3) + 8 * j; const LAS float* s = scr + (8 * c) * 33 + n;
;         u32x4 o; o.x = pkbf(s[0 * 33], s[1 * 33]); o.y = pkbf(s[2 * 33], s[3 * 33]); o.z = pkbf(s[4 * 33], s[5 * 33]); o.w = pkbf(s[6 * 33], s[7 * 33]);
;         *(u32x4*)(WT + (size_t)(n_dst + n) * K + k0 + 8 * c) = o;
;     }
;     asm volatile("s_waitcnt lgkmcnt(0)" ::: "memory");
	v_ashrrev_i32_e32 v139, 31, v138
	v_ashrrev_i32_e32 v137, 31, v136
	v_ashrrev_i32_e32 v143, 31, v142
	v_ashrrev_i32_e32 v141, 31, v140
	v_lshlrev_b64 v[112:113], 12, v[112:113]
	v_lshl_add_u64 v[114:115], v[36:37], 0, v[114:115]
	v_lshlrev_b64 v[116:117], 12, v[116:117]
	v_lshlrev_b64 v[118:119], 12, v[118:119]
	v_lshlrev_b64 v[120:121], 12, v[120:121]
	v_lshlrev_b64 v[122:123], 12, v[122:123]
	v_lshlrev_b64 v[124:125], 12, v[124:125]
	v_lshlrev_b64 v[126:127], 12, v[126:127]
	v_lshlrev_b64 v[128:129], 12, v[128:129]
	v_lshlrev_b64 v[130:131], 12, v[130:131]
	v_lshlrev_b64 v[132:133], 12, v[132:133]
	v_lshlrev_b64 v[134:135], 12, v[134:135]
	v_lshlrev_b64 v[136:137], 12, v[136:137]
	v_lshlrev_b64 v[138:139], 12, v[138:139]
	v_lshlrev_b64 v[140:141], 12, v[140:141]
	v_lshlrev_b64 v[142:143], 12, v[142:143]
	v_lshl_add_u64 v[112:113], v[36:37], 0, v[112:113]
	v_lshl_add_u64 v[118:119], v[36:37], 0, v[118:119]
	v_lshl_add_u64 v[116:117], v[36:37], 0, v[116:117]
	v_lshl_add_u64 v[122:123], v[36:37], 0, v[122:123]
	v_lshl_add_u64 v[120:121], v[36:37], 0, v[120:121]
	v_lshl_add_u64 v[126:127], v[36:37], 0, v[126:127]
	v_lshl_add_u64 v[124:125], v[36:37], 0, v[124:125]
	v_lshl_add_u64 v[130:131], v[36:37], 0, v[130:131]
	v_lshl_add_u64 v[128:129], v[36:37], 0, v[128:129]
	v_lshl_add_u64 v[134:135], v[36:37], 0, v[134:135]
	v_lshl_add_u64 v[132:133], v[36:37], 0, v[132:133]
	v_lshl_add_u64 v[138:139], v[36:37], 0, v[138:139]
	v_lshl_add_u64 v[136:137], v[36:37], 0, v[136:137]
	v_lshl_add_u64 v[142:143], v[36:37], 0, v[142:143]
	v_lshl_add_u64 v[140:141], v[36:37], 0, v[140:141]
	global_load_dword v157, v[114:115], off
	global_load_dword v158, v[112:113], off
	global_load_dword v159, v[118:119], off
	global_load_dword v160, v[116:117], off
	global_load_dword v161, v[122:123], off
	global_load_dword v162, v[120:121], off
	global_load_dword v163, v[126:127], off
	global_load_dword v164, v[124:125], off
	global_load_dword v165, v[130:131], off
	global_load_dword v166, v[128:129], off
	global_load_dword v167, v[134:135], off
	global_load_dword v168, v[132:133], off
	global_load_dword v169, v[138:139], off
	global_load_dword v170, v[136:137], off
	global_load_dword v171, v[142:143], off
	global_load_dword v172, v[140:141], off
	s_add_i32 s21, s21, 16
	s_add_i32 s20, s20, 16
	s_add_i32 s22, s22, -16
	s_cmp_lg_u32 s22, 0
	v_mad_u64_u32 v[48:49], s[44:45], v35, s24, v[6:7]
	v_mad_u64_u32 v[50:51], s[44:45], v4, s24, v[6:7]
	v_mad_u64_u32 v[52:53], s[44:45], v80, s24, v[6:7]
	v_mad_u64_u32 v[54:55], s[44:45], v47, s24, v[6:7]
	v_mad_u64_u32 v[56:57], s[44:45], v82, s24, v[6:7]
	v_mad_u64_u32 v[58:59], s[44:45], v81, s24, v[6:7]
	v_mad_u64_u32 v[60:61], s[44:45], v84, s24, v[6:7]
	v_mad_u64_u32 v[62:63], s[44:45], v83, s24, v[6:7]
	v_mad_u64_u32 v[64:65], s[44:45], v86, s24, v[6:7]
	v_mad_u64_u32 v[66:67], s[44:45], v85, s24, v[6:7]
	v_mad_u64_u32 v[68:69], s[44:45], v88, s24, v[6:7]
	v_mad_u64_u32 v[70:71], s[44:45], v87, s24, v[6:7]
	v_mad_u64_u32 v[72:73], s[44:45], v90, s24, v[6:7]
	v_mad_u64_u32 v[74:75], s[44:45], v89, s24, v[6:7]
	v_mad_u64_u32 v[76:77], s[44:45], v92, s24, v[6:7]
	v_mad_u64_u32 v[78:79], s[44:45], v91, s24, v[6:7]
	s_waitcnt vmcnt(16)
	ds_write_b32 v48, v93
	ds_write_b32 v50, v94
	ds_write_b32 v52, v95
	ds_write_b32 v54, v96
	ds_write_b32 v56, v97
	ds_write_b32 v58, v98
	ds_write_b32 v60, v99
	ds_write_b32 v62, v100
	ds_write_b32 v64, v101
	ds_write_b32 v66, v102
	ds_write_b32 v68, v103
	ds_write_b32 v70, v104
	ds_write_b32 v72, v105
	ds_write_b32 v74, v106
	ds_write_b32 v76, v107
	ds_write_b32 v78, v108
	v_mad_u64_u32 v[112:113], s[44:45], v175, s24, v[6:7]
	v_mad_u64_u32 v[114:115], s[44:45], v174, s24, v[6:7]
	v_mad_u64_u32 v[116:117], s[44:45], v144, s24, v[6:7]
	v_mad_u64_u32 v[118:119], s[44:45], v111, s24, v[6:7]
	v_mad_u64_u32 v[120:121], s[44:45], v146, s24, v[6:7]
	v_mad_u64_u32 v[122:123], s[44:45], v145, s24, v[6:7]
	v_mad_u64_u32 v[124:125], s[44:45], v148, s24, v[6:7]
	v_mad_u64_u32 v[126:127], s[44:45], v147, s24, v[6:7]
	v_mad_u64_u32 v[128:129], s[44:45], v150, s24, v[6:7]
	v_mad_u64_u32 v[130:131], s[44:45], v149, s24, v[6:7]
	v_mad_u64_u32 v[132:133], s[44:45], v152, s24, v[6:7]
	v_mad_u64_u32 v[134:135], s[44:45], v151, s24, v[6:7]
	v_mad_u64_u32 v[136:137], s[44:45], v154, s24, v[6:7]
	v_mad_u64_u32 v[138:139], s[44:45], v153, s24, v[6:7]
	v_mad_u64_u32 v[140:141], s[44:45], v156, s24, v[6:7]
	v_mad_u64_u32 v[142:143], s[44:45], v155, s24, v[6:7]
	s_waitcnt vmcnt(0)
	ds_write_b32 v112, v157
	ds_write_b32 v114, v158
	ds_write_b32 v116, v159
	ds_write_b32 v118, v160
	ds_write_b32 v120, v161
	ds_write_b32 v122, v162
	ds_write_b32 v124, v163
	ds_write_b32 v126, v164
	ds_write_b32 v128, v165
	ds_write_b32 v130, v166
	ds_write_b32 v132, v167
	ds_write_b32 v134, v168
	ds_write_b32 v136, v169
	ds_write_b32 v138, v170
	ds_write_b32 v140, v171
	ds_write_b32 v142, v172
	s_waitcnt lgkmcnt(0)
	ds_read2_b32 v[110:111], v38 offset1:33
	ds_read2_b32 v[112:113], v38 offset0:66 offset1:99
	ds_read2_b32 v[114:115], v38 offset0:132 offset1:165
	ds_read2_b32 v[116:117], v38 offset0:198 offset1:231
	ds_read2_b32 v[118:119], v38 offset0:8 offset1:41
	ds_read2_b32 v[120:121], v38 offset0:74 offset1:107
	ds_read2_b32 v[122:123], v38 offset0:140 offset1:173
	ds_read2_b32 v[124:125], v38 offset0:206 offset1:239
	ds_read2_b32 v[126:127], v38 offset0:16 offset1:49
	ds_read2_b32 v[128:129], v38 offset0:82 offset1:115
	ds_read2_b32 v[130:131], v38 offset0:148 offset1:181
	ds_read2_b32 v[132:133], v38 offset0:214 offset1:247
	ds_read2_b32 v[134:135], v38 offset0:24 offset1:57
	ds_read2_b32 v[136:137], v38 offset0:90 offset1:123
	ds_read2_b32 v[138:139], v38 offset0:156 offset1:189
	ds_read2_b32 v[140:141], v38 offset0:222 offset1:255
	s_waitcnt lgkmcnt(0)
	v_cvt_pk_bf16_f32 v48, v110, v111
	v_cvt_pk_bf16_f32 v49, v112, v113
	v_mov_b32_e32 v35, v5
	v_or_b32_e32 v3, v46, v7
	v_cvt_pk_bf16_f32 v50, v114, v115
	v_lshl_add_u64 v[52:53], v[34:35], 1, v[24:25]
	v_lshlrev_b32_e32 v4, 11, v3
	v_cvt_pk_bf16_f32 v51, v116, v117
	v_lshl_add_u64 v[34:35], v[52:53], 0, v[4:5]
	global_store_dwordx4 v[34:35], v[48:51], off
	s_nop 1
	v_cvt_pk_bf16_f32 v34, v118, v119
	v_or_b32_e32 v3, v46, v39
	v_cvt_pk_bf16_f32 v35, v120, v121
	v_lshlrev_b32_e32 v4, 11, v3
	v_cvt_pk_bf16_f32 v36, v122, v123
	v_cvt_pk_bf16_f32 v37, v124, v125
	v_lshl_add_u64 v[50:51], v[52:53], 0, v[4:5]
	global_store_dwordx4 v[50:51], v[34:37], off
	s_nop 1
	v_or_b32_e32 v3, v46, v40
	v_lshlrev_b32_e32 v4, 11, v3
	v_cvt_pk_bf16_f32 v34, v126, v127
	v_cvt_pk_bf16_f32 v35, v128, v129
	v_cvt_pk_bf16_f32 v36, v130, v131
	v_cvt_pk_bf16_f32 v37, v132, v133
	v_lshl_add_u64 v[50:51], v[52:53], 0, v[4:5]
	v_or_b32_e32 v3, v46, v41
	global_store_dwordx4 v[50:51], v[34:37], off
	s_nop 1
	v_lshlrev_b32_e32 v4, 11, v3
	v_lshl_add_u64 v[46:47], v[52:53], 0, v[4:5]
	v_cvt_pk_bf16_f32 v34, v134, v135
	v_cvt_pk_bf16_f32 v35, v136, v137
	v_cvt_pk_bf16_f32 v36, v138, v139
	v_cvt_pk_bf16_f32 v37, v140, v141
	global_store_dwordx4 v[46:47], v[34:37], off
	s_nop 1
	s_waitcnt lgkmcnt(0)

; __device__ __forceinline__ void transpose_item(const float* W, int K, int N, bf16_t* WT, int k0, int n_src, int n_dst, LAS float* scr, int lane) {
; #pragma unroll 8
;     for (int i = 0; i < 32; ++i) { const int kk = 2 * i + (lane >> 5); scr[kk * 33 + (lane & 31)] = W[(size_t)(k0 + kk) * N + n_src + (lane & 31)]; }
.LBB0_58:
	s_lshl_b32 s21, s0, 1
	s_lshl_b32 s22, s1, 1
	v_or_b32_e32 v35, s21, v1
	v_or_b32_e32 v78, s22, v2
	s_add_i32 s23, s21, 4
	s_add_i32 s43, s22, 4
	s_add_i32 s44, s21, 8
	s_add_i32 s45, s22, 8
	s_add_i32 s46, s21, 12
	s_add_i32 s47, s22, 12
	s_add_i32 s48, s21, 16
	s_add_i32 s49, s22, 16
	s_add_i32 s50, s21, 20
	s_add_i32 s51, s22, 20
	s_add_i32 s52, s21, 24
	s_add_i32 s53, s22, 24
	s_add_i32 s21, s21, 28
	s_add_i32 s22, s22, 28
	v_add_u32_e32 v46, v78, v34
	v_or_b32_e32 v79, s23, v1
	v_or_b32_e32 v80, s43, v2
	v_or_b32_e32 v81, s44, v1
	v_or_b32_e32 v82, s45, v2
	v_or_b32_e32 v83, s46, v1
	v_or_b32_e32 v84, s47, v2
	v_or_b32_e32 v85, s48, v1
	v_or_b32_e32 v86, s49, v2
	v_or_b32_e32 v87, s50, v1
	v_or_b32_e32 v88, s51, v2
	v_or_b32_e32 v89, s52, v1
	v_or_b32_e32 v90, s53, v2
	v_or_b32_e32 v91, s21, v1
	v_or_b32_e32 v92, s22, v2
	v_add_u32_e32 v48, v35, v3
	v_mad_i64_i32 v[46:47], s[22:23], v46, s41, v[36:37]
	v_add_u32_e32 v52, v79, v3
	v_add_u32_e32 v50, v80, v34
	v_add_u32_e32 v56, v81, v3
	v_add_u32_e32 v54, v82, v34
	v_add_u32_e32 v60, v83, v3
	v_add_u32_e32 v58, v84, v34
	v_add_u32_e32 v64, v85, v3
	v_add_u32_e32 v62, v86, v34
	v_add_u32_e32 v68, v87, v3
	v_add_u32_e32 v66, v88, v34
	v_add_u32_e32 v72, v89, v3
	v_add_u32_e32 v70, v90, v34
	v_add_u32_e32 v76, v91, v3
	v_add_u32_e32 v74, v92, v34
	v_mad_i64_i32 v[48:49], s[22:23], v48, s41, v[36:37]
	v_mad_i64_i32 v[50:51], s[22:23], v50, s41, v[36:37]
	v_mad_i64_i32 v[52:53], s[22:23], v52, s41, v[36:37]
	v_mad_i64_i32 v[54:55], s[22:23], v54, s41, v[36:37]
	v_mad_i64_i32 v[56:57], s[22:23], v56, s41, v[36:37]
	v_mad_i64_i32 v[58:59], s[22:23], v58, s41, v[36:37]
	v_mad_i64_i32 v[60:61], s[22:23], v60, s41, v[36:37]
	v_mad_i64_i32 v[62:63], s[22:23], v62, s41, v[36:37]
	v_mad_i64_i32 v[64:65], s[22:23], v64, s41, v[36:37]
	v_mad_i64_i32 v[66:67], s[22:23], v66, s41, v[36:37]
	v_mad_i64_i32 v[68:69], s[22:23], v68, s41, v[36:37]
	v_mad_i64_i32 v[70:71], s[22:23], v70, s41, v[36:37]
	v_mad_i64_i32 v[72:73], s[22:23], v72, s41, v[36:37]
	v_mad_i64_i32 v[74:75], s[22:23], v74, s41, v[36:37]
	v_mad_i64_i32 v[76:77], s[22:23], v76, s41, v[36:37]
	global_load_dword v93, v[46:47], off
	global_load_dword v94, v[48:49], off
	global_load_dword v95, v[50:51], off
	global_load_dword v96, v[52:53], off
	global_load_dword v97, v[54:55], off
	global_load_dword v98, v[56:57], off
	global_load_dword v99, v[58:59], off
	global_load_dword v100, v[60:61], off
	global_load_dword v101, v[62:63], off
	global_load_dword v102, v[64:65], off
	global_load_dword v103, v[66:67], off
	global_load_dword v104, v[68:69], off
	global_load_dword v105, v[70:71], off
	global_load_dword v106, v[72:73], off
	global_load_dword v107, v[74:75], off
	global_load_dword v108, v[76:77], off
	s_add_i32 s1, s1, 16
	s_add_i32 s0, s0, 16
	s_add_i32 s20, s20, -16
	s_cmp_lg_u32 s20, 0
	s_lshl_b32 s21, s0, 1
	s_lshl_b32 s22, s1, 1
	v_or_b32_e32 v174, s21, v1
	v_or_b32_e32 v142, s22, v2
	s_add_i32 s23, s21, 4
	s_add_i32 s43, s22, 4
	s_add_i32 s44, s21, 8
	s_add_i32 s45, s22, 8
	s_add_i32 s46, s21, 12
	s_add_i32 s47, s22, 12
	s_add_i32 s48, s21, 16
	s_add_i32 s49, s22, 16
	s_add_i32 s50, s21, 20
	s_add_i32 s51, s22, 20
	s_add_i32 s52, s21, 24
	s_add_i32 s53, s22, 24
	s_add_i32 s21, s21, 28
	s_add_i32 s22, s22, 28
	v_add_u32_e32 v110, v142, v34
	v_or_b32_e32 v143, s23, v1
	v_or_b32_e32 v144, s43, v2
	v_or_b32_e32 v145, s44, v1
	v_or_b32_e32 v146, s45, v2
	v_or_b32_e32 v147, s46, v1
	v_or_b32_e32 v148, s47, v2
	v_or_b32_e32 v149, s48, v1
	v_or_b32_e32 v150, s49, v2
	v_or_b32_e32 v151, s50, v1
	v_or_b32_e32 v152, s51, v2
	v_or_b32_e32 v153, s52, v1
	v_or_b32_e32 v154, s53, v2
	v_or_b32_e32 v155, s21, v1
	v_or_b32_e32 v156, s22, v2
	v_add_u32_e32 v112, v174, v3
	v_mad_i64_i32 v[110:111], s[22:23], v110, s41, v[36:37]
	v_add_u32_e32 v116, v143, v3
	v_add_u32_e32 v114, v144, v34
	v_add_u32_e32 v120, v145, v3
	v_add_u32_e32 v118, v146, v34
	v_add_u32_e32 v124, v147, v3
	v_add_u32_e32 v122, v148, v34
	v_add_u32_e32 v128, v149, v3
	v_add_u32_e32 v126, v150, v34
	v_add_u32_e32 v132, v151, v3
	v_add_u32_e32 v130, v152, v34
	v_add_u32_e32 v136, v153, v3
	v_add_u32_e32 v134, v154, v34
	v_add_u32_e32 v140, v155, v3
	v_add_u32_e32 v138, v156, v34
	v_mad_i64_i32 v[112:113], s[22:23], v112, s41, v[36:37]
	v_mad_i64_i32 v[114:115], s[22:23], v114, s41, v[36:37]
	v_mad_i64_i32 v[116:117], s[22:23], v116, s41, v[36:37]
	v_mad_i64_i32 v[118:119], s[22:23], v118, s41, v[36:37]
	v_mad_i64_i32 v[120:121], s[22:23], v120, s41, v[36:37]
	v_mad_i64_i32 v[122:123], s[22:23], v122, s41, v[36:37]
	v_mad_i64_i32 v[124:125], s[22:23], v124, s41, v[36:37]
	v_mad_i64_i32 v[126:127], s[22:23], v126, s41, v[36:37]
	v_mad_i64_i32 v[128:129], s[22:23], v128, s41, v[36:37]
	v_mad_i64_i32 v[130:131], s[22:23], v130, s41, v[36:37]
	v_mad_i64_i32 v[132:133], s[22:23], v132, s41, v[36:37]
	v_mad_i64_i32 v[134:135], s[22:23], v134, s41, v[36:37]
	v_mad_i64_i32 v[136:137], s[22:23], v136, s41, v[36:37]
	v_mad_i64_i32 v[138:139], s[22:23], v138, s41, v[36:37]
	v_mad_i64_i32 v[140:141], s[22:23], v140, s41, v[36:37]
	global_load_dword v157, v[110:111], off
	global_load_dword v158, v[112:113], off
	global_load_dword v159, v[114:115], off
	global_load_dword v160, v[116:117], off
	global_load_dword v161, v[118:119], off
	global_load_dword v162, v[120:121], off
	global_load_dword v163, v[122:123], off
	global_load_dword v164, v[124:125], off
	global_load_dword v165, v[126:127], off
	global_load_dword v166, v[128:129], off
	global_load_dword v167, v[130:131], off
	global_load_dword v168, v[132:133], off
	global_load_dword v169, v[134:135], off
	global_load_dword v170, v[136:137], off
	global_load_dword v171, v[138:139], off
	global_load_dword v172, v[140:141], off
	s_add_i32 s1, s1, 16
	s_add_i32 s0, s0, 16
	s_add_i32 s20, s20, -16
	s_cmp_lg_u32 s20, 0
	v_mad_u64_u32 v[46:47], s[22:23], v78, s24, v[6:7]
	v_mad_u64_u32 v[48:49], s[22:23], v35, s24, v[6:7]
	v_mad_u64_u32 v[50:51], s[22:23], v80, s24, v[6:7]
	v_mad_u64_u32 v[52:53], s[22:23], v79, s24, v[6:7]
	v_mad_u64_u32 v[54:55], s[22:23], v82, s24, v[6:7]
	v_mad_u64_u32 v[56:57], s[22:23], v81, s24, v[6:7]
	v_mad_u64_u32 v[58:59], s[22:23], v84, s24, v[6:7]
	v_mad_u64_u32 v[60:61], s[22:23], v83, s24, v[6:7]
	v_mad_u64_u32 v[62:63], s[22:23], v86, s24, v[6:7]
	v_mad_u64_u32 v[64:65], s[22:23], v85, s24, v[6:7]
	v_mad_u64_u32 v[66:67], s[22:23], v88, s24, v[6:7]
	v_mad_u64_u32 v[68:69], s[22:23], v87, s24, v[6:7]
	v_mad_u64_u32 v[70:71], s[22:23], v90, s24, v[6:7]
	v_mad_u64_u32 v[72:73], s[22:23], v89, s24, v[6:7]
	v_mad_u64_u32 v[74:75], s[22:23], v92, s24, v[6:7]
	v_mad_u64_u32 v[76:77], s[22:23], v91, s24, v[6:7]
	s_waitcnt vmcnt(16)
; #define LAS __attribute__((address_space(3)))
; #define LAS __attribute__((address_space(3)))
; __device__ __forceinline__ unsigned pkbf(float lo, float hi) { return pg8::cvt_pk_bf16(lo, hi); }
; __device__ __forceinline__ void transpose_item(const float* W, int K, int N, bf16_t* WT, int k0, int n_src, int n_dst, LAS float* scr, int lane) {
;     ...
;     for (int i = 0; i < 32; ++i) { const int kk = 2 * i + (lane >> 5); scr[kk * 33 + (lane & 31)] = W[(size_t)(k0 + kk) * N + n_src + (lane & 31)]; }
;     asm volatile("s_waitcnt lgkmcnt(0)" ::: "memory");
;     const int c = lane & 7;
; #pragma unroll
;     for (int j = 0; j < 4; ++j) {
;         const int n = (lane >> 3) + 8 * j; const LAS float* s = scr + (8 * c) * 33 + n;
;         u32x4 o; o.x = pkbf(s[0 * 33], s[1 * 33]); o.y = pkbf(s[2 * 33], s[3 * 33]); o.z = pkbf(s[4 * 33], s[5 * 33]); o.w = pkbf(s[6 * 33], s[7 * 33]);
;         *(u32x4*)(WT + (size_t)(n_dst + n) * K + k0 + 8 * c) = o;
;     }
;     asm volatile("s_waitcnt lgkmcnt(0)" ::: "memory");
	ds_write_b32 v46, v93
	ds_write_b32 v48, v94
	ds_write_b32 v50, v95
	ds_write_b32 v52, v96
	ds_write_b32 v54, v97
	ds_write_b32 v56, v98
	ds_write_b32 v58, v99
	ds_write_b32 v60, v100
	ds_write_b32 v62, v101
	ds_write_b32 v64, v102
	ds_write_b32 v66, v103
	ds_write_b32 v68, v104
	ds_write_b32 v70, v105
	ds_write_b32 v72, v106
	ds_write_b32 v74, v107
	ds_write_b32 v76, v108
	v_mad_u64_u32 v[110:111], s[22:23], v142, s24, v[6:7]
	v_mad_u64_u32 v[112:113], s[22:23], v174, s24, v[6:7]
	v_mad_u64_u32 v[114:115], s[22:23], v144, s24, v[6:7]
	v_mad_u64_u32 v[116:117], s[22:23], v143, s24, v[6:7]
	v_mad_u64_u32 v[118:119], s[22:23], v146, s24, v[6:7]
	v_mad_u64_u32 v[120:121], s[22:23], v145, s24, v[6:7]
	v_mad_u64_u32 v[122:123], s[22:23], v148, s24, v[6:7]
	v_mad_u64_u32 v[124:125], s[22:23], v147, s24, v[6:7]
	v_mad_u64_u32 v[126:127], s[22:23], v150, s24, v[6:7]
	v_mad_u64_u32 v[128:129], s[22:23], v149, s24, v[6:7]
	v_mad_u64_u32 v[130:131], s[22:23], v152, s24, v[6:7]
	v_mad_u64_u32 v[132:133], s[22:23], v151, s24, v[6:7]
	v_mad_u64_u32 v[134:135], s[22:23], v154, s24, v[6:7]
	v_mad_u64_u32 v[136:137], s[22:23], v153, s24, v[6:7]
	v_mad_u64_u32 v[138:139], s[22:23], v156, s24, v[6:7]
	v_mad_u64_u32 v[140:141], s[22:23], v155, s24, v[6:7]
	s_waitcnt vmcnt(0)
	ds_write_b32 v110, v157
	ds_write_b32 v112, v158
	ds_write_b32 v114, v159
	ds_write_b32 v116, v160
	ds_write_b32 v118, v161
	ds_write_b32 v120, v162
	ds_write_b32 v122, v163
	ds_write_b32 v124, v164
	ds_write_b32 v126, v165
	ds_write_b32 v128, v166
	ds_write_b32 v130, v167
	ds_write_b32 v132, v168
	ds_write_b32 v134, v169
	ds_write_b32 v136, v170
	ds_write_b32 v138, v171
	ds_write_b32 v140, v172
	s_waitcnt lgkmcnt(0)
	ds_read2_b32 v[110:111], v38 offset1:33
	ds_read2_b32 v[112:113], v38 offset0:66 offset1:99
	ds_read2_b32 v[114:115], v38 offset0:132 offset1:165
	ds_read2_b32 v[116:117], v38 offset0:198 offset1:231
	ds_read2_b32 v[118:119], v38 offset0:8 offset1:41
	ds_read2_b32 v[120:121], v38 offset0:74 offset1:107
	ds_read2_b32 v[122:123], v38 offset0:140 offset1:173
	ds_read2_b32 v[124:125], v38 offset0:206 offset1:239
	ds_read2_b32 v[126:127], v38 offset0:16 offset1:49
	ds_read2_b32 v[128:129], v38 offset0:82 offset1:115
	ds_read2_b32 v[130:131], v38 offset0:148 offset1:181
	ds_read2_b32 v[132:133], v38 offset0:214 offset1:247
	ds_read2_b32 v[134:135], v38 offset0:24 offset1:57
	ds_read2_b32 v[136:137], v38 offset0:90 offset1:123
	ds_read2_b32 v[138:139], v38 offset0:156 offset1:189
	ds_read2_b32 v[140:141], v38 offset0:222 offset1:255
	s_waitcnt lgkmcnt(0)
	v_cvt_pk_bf16_f32 v46, v110, v111
	v_cvt_pk_bf16_f32 v47, v112, v113
	v_or_b32_e32 v50, v4, v7
	v_cvt_pk_bf16_f32 v48, v114, v115
	v_ashrrev_i32_e32 v35, 31, v34
	v_ashrrev_i32_e32 v51, 31, v50
	v_lshl_add_u64 v[52:53], v[34:35], 1, v[18:19]
	v_cvt_pk_bf16_f32 v49, v116, v117
	v_lshlrev_b64 v[36:37], 11, v[50:51]
	v_lshl_add_u64 v[36:37], v[52:53], 0, v[36:37]
	global_store_dwordx4 v[36:37], v[46:49], off
	s_nop 1
	v_cvt_pk_bf16_f32 v34, v118, v119
	v_or_b32_e32 v48, v4, v39
	v_ashrrev_i32_e32 v49, 31, v48
	v_lshlrev_b64 v[48:49], 11, v[48:49]
	v_cvt_pk_bf16_f32 v35, v120, v121
	v_lshl_add_u64 v[48:49], v[52:53], 0, v[48:49]
	v_cvt_pk_bf16_f32 v36, v122, v123
	v_cvt_pk_bf16_f32 v37, v124, v125
	global_store_dwordx4 v[48:49], v[34:37], off
	s_nop 1
	v_or_b32_e32 v48, v4, v40
	v_cvt_pk_bf16_f32 v34, v126, v127
	v_ashrrev_i32_e32 v49, 31, v48
	v_cvt_pk_bf16_f32 v35, v128, v129
	v_lshlrev_b64 v[48:49], 11, v[48:49]
	v_cvt_pk_bf16_f32 v36, v130, v131
	v_cvt_pk_bf16_f32 v37, v132, v133
	v_lshl_add_u64 v[48:49], v[52:53], 0, v[48:49]
	global_store_dwordx4 v[48:49], v[34:37], off
	s_nop 1
	v_or_b32_e32 v48, v4, v41
	v_ashrrev_i32_e32 v49, 31, v48
	v_cvt_pk_bf16_f32 v34, v134, v135
	v_cvt_pk_bf16_f32 v35, v136, v137
	v_cvt_pk_bf16_f32 v36, v138, v139
	v_lshlrev_b64 v[48:49], 11, v[48:49]
	v_cvt_pk_bf16_f32 v37, v140, v141
	v_lshl_add_u64 v[46:47], v[52:53], 0, v[48:49]
	global_store_dwordx4 v[46:47], v[34:37], off
	s_nop 1
	s_waitcnt lgkmcnt(0)
	s_branch .LBB0_29
